# kswz16 plus P8 tile4 sub-tiles 2,3: K fragment ds_read_b128 software-pipelined 3 fragments ahead through a 5-buffer ring (v244-v255 added, next_free_vgpr 256)
# speedup vs baseline: 1.0043x; 1.0043x over previous
.LBB0_1041:
	ds_read_b128 v[240:243], v231 offset:32768
	ds_read_b128 v[244:247], v231 offset:40960
	ds_read_b128 v[248:251], v230 offset:32768
	ds_read_b128 v[252:255], v230 offset:40960
	ds_read_b128 v[236:239], v229 offset:32768
	v_cmp_ge_f32_e64 s[12:13], s88, v222
	v_sub_f32_e32 v100, v100, v234
	v_sub_f32_e32 v116, v116, v234
	v_cndmask_b32_e64 v68, v233, 0, s[12:13]
	v_mov_b32_e32 v69, v68
	v_mov_b32_e32 v70, v68
	v_mov_b32_e32 v71, v68
	v_mov_b32_e32 v72, v68
	v_mov_b32_e32 v73, v68
	v_mov_b32_e32 v74, v68
	v_mov_b32_e32 v75, v68
	v_mov_b32_e32 v76, v68
	v_mov_b32_e32 v77, v68
	v_mov_b32_e32 v78, v68
	v_mov_b32_e32 v79, v68
	v_mov_b32_e32 v80, v68
	v_mov_b32_e32 v81, v68
	v_mov_b32_e32 v82, v68
	v_mov_b32_e32 v83, v68
	v_exp_f32_e32 v116, v116
	v_mov_b32_e32 v228, 0
	s_waitcnt lgkmcnt(4)
	v_mfma_f32_32x32x16_bf16 v[84:99], v[240:243], v[160:163], v[68:83]
	s_waitcnt lgkmcnt(3)
	v_mfma_f32_32x32x16_bf16 v[68:83], v[244:247], v[160:163], v[68:83]
	ds_read_b128 v[240:243], v229 offset:40960
	s_waitcnt lgkmcnt(3)
	v_mfma_f32_32x32x16_bf16 v[84:99], v[248:251], v[156:159], v[84:99]
	ds_read_b128 v[244:247], v227 offset:32768
	s_waitcnt lgkmcnt(3)
	v_mfma_f32_32x32x16_bf16 v[68:83], v[252:255], v[156:159], v[68:83]
	ds_read_b128 v[248:251], v227 offset:40960
	s_waitcnt lgkmcnt(3)
	v_mfma_f32_32x32x16_bf16 v[84:99], v[236:239], v[152:155], v[84:99]
	ds_read_b128 v[252:255], v226 offset:32768
	s_waitcnt lgkmcnt(3)
	v_mfma_f32_32x32x16_bf16 v[68:83], v[240:243], v[152:155], v[68:83]
	ds_read_b128 v[236:239], v226 offset:40960
	s_waitcnt lgkmcnt(3)
	v_mfma_f32_32x32x16_bf16 v[84:99], v[244:247], v[148:151], v[84:99]
	ds_read_b128 v[240:243], v225 offset:32768
	s_waitcnt lgkmcnt(3)
	v_mfma_f32_32x32x16_bf16 v[68:83], v[248:251], v[148:151], v[68:83]
	ds_read_b128 v[244:247], v225 offset:40960
	s_waitcnt lgkmcnt(3)
	v_mfma_f32_32x32x16_bf16 v[84:99], v[252:255], v[144:147], v[84:99]
	ds_read_b128 v[248:251], v224 offset:32768
	s_waitcnt lgkmcnt(3)
	v_mfma_f32_32x32x16_bf16 v[68:83], v[236:239], v[144:147], v[68:83]
	ds_read_b128 v[252:255], v224 offset:40960
	s_waitcnt lgkmcnt(3)
	v_mfma_f32_32x32x16_bf16 v[84:99], v[240:243], v[140:143], v[84:99]
	ds_read_b128 v[236:239], v2 offset:32768
	s_waitcnt lgkmcnt(3)
	v_mfma_f32_32x32x16_bf16 v[68:83], v[244:247], v[140:143], v[68:83]
	ds_read_b128 v[240:243], v2 offset:40960
	s_waitcnt lgkmcnt(3)
	v_mfma_f32_32x32x16_bf16 v[84:99], v[248:251], v[136:139], v[84:99]
	s_waitcnt lgkmcnt(2)
	v_mfma_f32_32x32x16_bf16 v[68:83], v[252:255], v[136:139], v[68:83]
	s_waitcnt lgkmcnt(1)
	v_mfma_f32_32x32x16_bf16 v[84:99], v[236:239], v[132:135], v[84:99]
	v_exp_f32_e32 v236, v100
	v_sub_f32_e32 v100, v117, v234
	v_exp_f32_e32 v117, v100
	v_sub_f32_e32 v100, v101, v234
	v_exp_f32_e32 v237, v100
	v_sub_f32_e32 v100, v118, v234
	v_exp_f32_e32 v118, v100
	v_sub_f32_e32 v100, v102, v234
	v_exp_f32_e32 v238, v100
	v_sub_f32_e32 v100, v119, v234
	v_exp_f32_e32 v119, v100
	v_sub_f32_e32 v100, v103, v234
	v_exp_f32_e32 v239, v100
	v_sub_f32_e32 v100, v120, v234
	v_exp_f32_e32 v102, v100
	v_sub_f32_e32 v100, v104, v234
	v_exp_f32_e32 v120, v100
	v_sub_f32_e32 v100, v121, v234
	v_exp_f32_e32 v103, v100
	v_sub_f32_e32 v100, v105, v234
	v_exp_f32_e32 v121, v100
	v_sub_f32_e32 v100, v122, v234
	v_exp_f32_e32 v104, v100
	v_sub_f32_e32 v100, v106, v234
	v_exp_f32_e32 v122, v100
	v_sub_f32_e32 v100, v123, v234
	v_exp_f32_e32 v105, v100
	v_sub_f32_e32 v100, v107, v234
	v_exp_f32_e32 v123, v100
	v_sub_f32_e32 v100, v124, v234
	v_exp_f32_e32 v106, v100
	v_sub_f32_e32 v100, v108, v234
	v_exp_f32_e32 v124, v100
	v_sub_f32_e32 v100, v125, v234
	v_exp_f32_e32 v107, v100
	v_sub_f32_e32 v100, v109, v234
	v_exp_f32_e32 v125, v100
	v_sub_f32_e32 v100, v126, v234
	v_exp_f32_e32 v108, v100
	v_sub_f32_e32 v100, v110, v234
	v_exp_f32_e32 v126, v100
	v_sub_f32_e32 v100, v127, v234
	v_exp_f32_e32 v109, v100
	v_sub_f32_e32 v100, v111, v234
	v_exp_f32_e32 v127, v100
	v_sub_f32_e32 v100, v128, v234
	v_exp_f32_e32 v110, v100
	v_sub_f32_e32 v100, v112, v234
	v_exp_f32_e32 v128, v100
	v_sub_f32_e32 v100, v129, v234
	v_exp_f32_e32 v111, v100
	v_sub_f32_e32 v100, v113, v234
	v_exp_f32_e32 v129, v100
	v_sub_f32_e32 v100, v130, v234
	v_exp_f32_e32 v112, v100
	v_sub_f32_e32 v100, v114, v234
	v_exp_f32_e32 v130, v100
	v_sub_f32_e32 v100, v131, v234
	v_exp_f32_e32 v113, v100
	v_sub_f32_e32 v100, v115, v234
	v_exp_f32_e32 v131, v100
	s_waitcnt lgkmcnt(0)
	v_mfma_f32_32x32x16_bf16 v[68:83], v[240:243], v[132:135], v[68:83]
	v_add_f32_e64 v100, v108, v126
	v_add_f32_e64 v101, v109, v127
	v_add_f32_e64 v114, v118, v238
	v_add_f32_e64 v115, v119, v239
	v_add_f32_e64 v234, v112, v130
	v_add_f32_e64 v235, v113, v131
	v_pk_add_f32 v[240:241], v[104:105], v[122:123]
	v_pk_add_f32 v[242:243], v[106:107], v[124:125]
	v_pk_add_f32 v[244:245], v[116:117], v[236:237]
	v_pk_add_f32 v[246:247], v[110:111], v[128:129]
	v_pk_add_f32 v[248:249], v[102:103], v[120:121]
	v_pk_add_f32 v[242:243], v[244:245], v[242:243]
	v_pk_add_f32 v[246:247], v[248:249], v[246:247]
	v_pk_add_f32 v[234:235], v[240:241], v[234:235]
	v_pk_add_f32 v[100:101], v[114:115], v[100:101]
	v_pk_add_f32 v[114:115], v[242:243], v[246:247]
	v_pk_add_f32 v[100:101], v[100:101], v[234:235]
	s_nop 0
	v_pk_mov_b32 v[234:235], v[114:115], v[100:101] op_sel:[1,0]
	v_mov_b32_e32 v115, v101
	v_pk_add_f32 v[100:101], v[234:235], v[114:115]
	s_nop 0
	v_pk_add_f32 v[100:101], v[100:101], v[100:101] op_sel:[0,1] op_sel_hi:[1,0]
	s_nop 0
	v_mov_b32_e32 v101, v100
	s_nop 1
	v_permlane32_swap_b32_e32 v100, v101
	v_add_f32_e32 v100, v100, v101
	v_add_f32_e32 v232, v232, v100
	v_cvt_pk_bf16_f32 v100, v116, v117
	v_cvt_pk_bf16_f32 v101, v118, v119
	v_cvt_pk_bf16_f32 v102, v102, v103
	v_cvt_pk_bf16_f32 v103, v104, v105
	v_cvt_pk_bf16_f32 v104, v106, v107
	v_cvt_pk_bf16_f32 v105, v108, v109
	v_cvt_pk_bf16_f32 v106, v110, v111
	v_cvt_pk_bf16_f32 v107, v112, v113
	v_cvt_pk_bf16_f32 v108, v236, v237
	v_cvt_pk_bf16_f32 v109, v238, v239
	v_cvt_pk_bf16_f32 v110, v120, v121
	v_cvt_pk_bf16_f32 v111, v122, v123
	v_cvt_pk_bf16_f32 v112, v124, v125
	v_cvt_pk_bf16_f32 v113, v126, v127
	v_cvt_pk_bf16_f32 v114, v128, v129
	v_cvt_pk_bf16_f32 v115, v130, v131
	ds_read_b64_tr_b16 v[116:117], v189 offset:0
	ds_read_b64_tr_b16 v[118:119], v189 offset:0x800
	ds_read_b64_tr_b16 v[120:121], v189 offset:0x1000
	ds_read_b64_tr_b16 v[122:123], v189 offset:0x1800
	ds_read_b64_tr_b16 v[124:125], v189 offset:0x2000
	ds_read_b64_tr_b16 v[126:127], v189 offset:0x2800
	ds_read_b64_tr_b16 v[128:129], v189 offset:0x3000
	ds_read_b64_tr_b16 v[130:131], v189 offset:0x3800
	s_waitcnt lgkmcnt(0)
	s_nop 0
	v_permlane32_swap_b32_e32 v100, v102
	v_permlane32_swap_b32_e32 v101, v103
	v_permlane32_swap_b32_e32 v104, v106
	v_permlane32_swap_b32_e32 v105, v107
	v_permlane32_swap_b32_e32 v108, v110
	v_permlane32_swap_b32_e32 v109, v111
	v_permlane32_swap_b32_e32 v112, v114
	v_permlane32_swap_b32_e32 v113, v115
	v_mfma_f32_32x32x16_bf16 v[52:67], v[116:119], v[100:103], v[52:67]
	ds_read_b64_tr_b16 v[116:117], v189 offset:0x200
	ds_read_b64_tr_b16 v[118:119], v189 offset:0xa00
	v_mfma_f32_32x32x16_bf16 v[52:67], v[120:123], v[104:107], v[52:67]
	ds_read_b64_tr_b16 v[120:121], v189 offset:0x1200
	ds_read_b64_tr_b16 v[122:123], v189 offset:0x1a00
	v_mfma_f32_32x32x16_bf16 v[52:67], v[124:127], v[108:111], v[52:67]
	ds_read_b64_tr_b16 v[124:125], v189 offset:0x2200
	ds_read_b64_tr_b16 v[126:127], v189 offset:0x2a00
	ds_read_b64_tr_b16 v[234:235], v189 offset:0x3200
	ds_read_b64_tr_b16 v[236:237], v189 offset:0x3a00
	s_waitcnt lgkmcnt(0)
	v_mfma_f32_32x32x16_bf16 v[52:67], v[128:131], v[112:115], v[52:67]
	v_mfma_f32_32x32x16_bf16 v[36:51], v[116:119], v[100:103], v[36:51]
	ds_read_b64_tr_b16 v[116:117], v189 offset:0x400
	ds_read_b64_tr_b16 v[118:119], v189 offset:0xc00
	v_mfma_f32_32x32x16_bf16 v[36:51], v[120:123], v[104:107], v[36:51]
	ds_read_b64_tr_b16 v[120:121], v189 offset:0x1400
	ds_read_b64_tr_b16 v[122:123], v189 offset:0x1c00
	v_mfma_f32_32x32x16_bf16 v[36:51], v[124:127], v[108:111], v[36:51]
	ds_read_b64_tr_b16 v[124:125], v189 offset:0x2400
	ds_read_b64_tr_b16 v[126:127], v189 offset:0x2c00
	ds_read_b64_tr_b16 v[128:129], v189 offset:0x3400
	ds_read_b64_tr_b16 v[130:131], v189 offset:0x3c00
	s_waitcnt lgkmcnt(0)
	v_mfma_f32_32x32x16_bf16 v[36:51], v[234:237], v[112:115], v[36:51]
	v_mfma_f32_32x32x16_bf16 v[20:35], v[116:119], v[100:103], v[20:35]
	ds_read_b64_tr_b16 v[116:117], v189 offset:0x600
	ds_read_b64_tr_b16 v[118:119], v189 offset:0xe00
	v_mfma_f32_32x32x16_bf16 v[20:35], v[120:123], v[104:107], v[20:35]
	ds_read_b64_tr_b16 v[120:121], v189 offset:0x1600
	ds_read_b64_tr_b16 v[122:123], v189 offset:0x1e00
	v_mfma_f32_32x32x16_bf16 v[20:35], v[124:127], v[108:111], v[20:35]
	ds_read_b64_tr_b16 v[124:125], v189 offset:0x2600
	ds_read_b64_tr_b16 v[126:127], v189 offset:0x2e00
	ds_read_b64_tr_b16 v[234:235], v189 offset:0x3600
	ds_read_b64_tr_b16 v[236:237], v189 offset:0x3e00
	s_waitcnt lgkmcnt(0)
	v_mfma_f32_32x32x16_bf16 v[20:35], v[128:131], v[112:115], v[20:35]
	v_mfma_f32_32x32x16_bf16 v[4:19], v[116:119], v[100:103], v[4:19]
	v_max_f32_e32 v128, v85, v85
	v_max_f32_e32 v129, v84, v84
	v_max_f32_e32 v128, v129, v128
	v_max3_f32 v128, v128, v86, v87
	v_max3_f32 v128, v128, v88, v89
	v_max3_f32 v100, v128, v90, v91
	v_max3_f32 v100, v100, v92, v93
	v_mfma_f32_32x32x16_bf16 v[4:19], v[120:123], v[104:107], v[4:19]
	v_max3_f32 v100, v100, v94, v95
	v_max3_f32 v100, v100, v96, v97
	v_max3_f32 v100, v100, v98, v99
	v_max3_f32 v100, v100, v68, v69
	v_max3_f32 v100, v100, v70, v71
	v_max3_f32 v100, v100, v72, v73
	v_max3_f32 v100, v100, v74, v75
	v_mfma_f32_32x32x16_bf16 v[4:19], v[124:127], v[108:111], v[4:19]
	v_max3_f32 v100, v100, v76, v77
	v_max3_f32 v100, v100, v78, v79
	v_max3_f32 v100, v100, v80, v81
	v_max3_f32 v100, v100, v82, v83
	v_mov_b32_e32 v101, v100
	s_nop 1
	v_permlane32_swap_b32_e32 v100, v101
	v_mfma_f32_32x32x16_bf16 v[4:19], v[234:237], v[112:115], v[4:19]
	v_max_f32_e32 v101, v101, v101
	v_max_f32_e32 v100, v100, v100
	v_max_f32_e32 v100, v100, v101
	v_cmp_lt_f32_e32 vcc, s89, v100
	s_or_b64 vcc, s[12:13], vcc
	s_cbranch_vccz .LBB0_1043
	v_cndmask_b32_e32 v234, 0, v100, vcc
	v_exp_f32_e64 v100, -v234
	v_cndmask_b32_e64 v101, v222, 0, s[12:13]
	v_add_f32_e32 v222, v101, v234
	v_xor_b32_e32 v233, 0x80000000, v222
	v_cndmask_b32_e64 v100, v100, 0, s[12:13]
	v_mul_f32_e32 v232, v232, v100
	v_pk_mul_f32 v[66:67], v[66:67], v[100:101] op_sel_hi:[1,0]
	v_pk_mul_f32 v[64:65], v[64:65], v[100:101] op_sel_hi:[1,0]
	v_pk_mul_f32 v[62:63], v[62:63], v[100:101] op_sel_hi:[1,0]
	v_pk_mul_f32 v[60:61], v[60:61], v[100:101] op_sel_hi:[1,0]
	v_pk_mul_f32 v[58:59], v[58:59], v[100:101] op_sel_hi:[1,0]
	v_pk_mul_f32 v[56:57], v[56:57], v[100:101] op_sel_hi:[1,0]
	v_pk_mul_f32 v[54:55], v[54:55], v[100:101] op_sel_hi:[1,0]
	v_pk_mul_f32 v[52:53], v[52:53], v[100:101] op_sel_hi:[1,0]
	v_pk_mul_f32 v[50:51], v[50:51], v[100:101] op_sel_hi:[1,0]
	v_pk_mul_f32 v[48:49], v[48:49], v[100:101] op_sel_hi:[1,0]
	v_pk_mul_f32 v[46:47], v[46:47], v[100:101] op_sel_hi:[1,0]
	v_pk_mul_f32 v[44:45], v[44:45], v[100:101] op_sel_hi:[1,0]
	v_pk_mul_f32 v[42:43], v[42:43], v[100:101] op_sel_hi:[1,0]
	v_pk_mul_f32 v[40:41], v[40:41], v[100:101] op_sel_hi:[1,0]
	v_pk_mul_f32 v[38:39], v[38:39], v[100:101] op_sel_hi:[1,0]
	v_pk_mul_f32 v[36:37], v[36:37], v[100:101] op_sel_hi:[1,0]
	v_pk_mul_f32 v[34:35], v[34:35], v[100:101] op_sel_hi:[1,0]
	v_pk_mul_f32 v[32:33], v[32:33], v[100:101] op_sel_hi:[1,0]
	v_pk_mul_f32 v[30:31], v[30:31], v[100:101] op_sel_hi:[1,0]
	v_pk_mul_f32 v[28:29], v[28:29], v[100:101] op_sel_hi:[1,0]
	v_pk_mul_f32 v[26:27], v[26:27], v[100:101] op_sel_hi:[1,0]
	v_pk_mul_f32 v[24:25], v[24:25], v[100:101] op_sel_hi:[1,0]
	v_pk_mul_f32 v[22:23], v[22:23], v[100:101] op_sel_hi:[1,0]
	v_pk_mul_f32 v[20:21], v[20:21], v[100:101] op_sel_hi:[1,0]
	v_pk_mul_f32 v[18:19], v[18:19], v[100:101] op_sel_hi:[1,0]
	v_pk_mul_f32 v[16:17], v[16:17], v[100:101] op_sel_hi:[1,0]
	v_pk_mul_f32 v[14:15], v[14:15], v[100:101] op_sel_hi:[1,0]
	v_pk_mul_f32 v[12:13], v[12:13], v[100:101] op_sel_hi:[1,0]
	v_pk_mul_f32 v[10:11], v[10:11], v[100:101] op_sel_hi:[1,0]
	v_pk_mul_f32 v[8:9], v[8:9], v[100:101] op_sel_hi:[1,0]
	v_pk_mul_f32 v[6:7], v[6:7], v[100:101] op_sel_hi:[1,0]
	v_pk_mul_f32 v[4:5], v[4:5], v[100:101] op_sel_hi:[1,0]
	s_branch .LBB0_1044

.LBB0_1044:
	ds_read_b128 v[236:239], v231 offset:49152
	ds_read_b128 v[240:243], v231 offset:57344
	ds_read_b128 v[244:247], v230 offset:49152
	ds_read_b128 v[248:251], v230 offset:57344
	ds_read_b128 v[252:255], v229 offset:49152
	v_cmp_ge_f32_e64 s[12:13], s88, v222
	s_nop 1
	v_cndmask_b32_e64 v100, v233, 0, s[12:13]
	v_mov_b32_e32 v101, v100
	v_mov_b32_e32 v102, v100
	v_mov_b32_e32 v103, v100
	v_mov_b32_e32 v104, v100
	v_mov_b32_e32 v105, v100
	v_mov_b32_e32 v106, v100
	v_mov_b32_e32 v107, v100
	v_mov_b32_e32 v108, v100
	v_mov_b32_e32 v109, v100
	v_mov_b32_e32 v110, v100
	v_mov_b32_e32 v111, v100
	v_mov_b32_e32 v112, v100
	v_mov_b32_e32 v113, v100
	v_mov_b32_e32 v114, v100
	v_mov_b32_e32 v115, v100
	s_nop 0
	s_waitcnt lgkmcnt(4)
	v_mfma_f32_32x32x16_bf16 v[116:131], v[236:239], v[160:163], v[100:115]
	s_waitcnt lgkmcnt(3)
	v_mfma_f32_32x32x16_bf16 v[100:115], v[240:243], v[160:163], v[100:115]
	ds_read_b128 v[236:239], v229 offset:57344
	s_waitcnt lgkmcnt(3)
	v_mfma_f32_32x32x16_bf16 v[116:131], v[244:247], v[156:159], v[116:131]
	ds_read_b128 v[240:243], v227 offset:49152
	s_waitcnt lgkmcnt(3)
	v_mfma_f32_32x32x16_bf16 v[100:115], v[248:251], v[156:159], v[100:115]
	ds_read_b128 v[244:247], v227 offset:57344
	s_waitcnt lgkmcnt(3)
	v_mfma_f32_32x32x16_bf16 v[116:131], v[252:255], v[152:155], v[116:131]
	ds_read_b128 v[248:251], v226 offset:49152
	s_waitcnt lgkmcnt(3)
	v_mfma_f32_32x32x16_bf16 v[100:115], v[236:239], v[152:155], v[100:115]
	ds_read_b128 v[252:255], v226 offset:57344
	s_waitcnt lgkmcnt(3)
	v_mfma_f32_32x32x16_bf16 v[116:131], v[240:243], v[148:151], v[116:131]
	ds_read_b128 v[236:239], v225 offset:49152
	s_waitcnt lgkmcnt(3)
	v_mfma_f32_32x32x16_bf16 v[100:115], v[244:247], v[148:151], v[100:115]
	ds_read_b128 v[240:243], v225 offset:57344
	s_waitcnt lgkmcnt(3)
	v_mfma_f32_32x32x16_bf16 v[116:131], v[248:251], v[144:147], v[116:131]
	ds_read_b128 v[244:247], v224 offset:49152
	s_waitcnt lgkmcnt(3)
	v_mfma_f32_32x32x16_bf16 v[100:115], v[252:255], v[144:147], v[100:115]
	ds_read_b128 v[248:251], v224 offset:57344
	s_waitcnt lgkmcnt(3)
	v_mfma_f32_32x32x16_bf16 v[116:131], v[236:239], v[140:143], v[116:131]
	ds_read_b128 v[252:255], v2 offset:49152
	s_waitcnt lgkmcnt(3)
	v_mfma_f32_32x32x16_bf16 v[100:115], v[240:243], v[140:143], v[100:115]
	ds_read_b128 v[236:239], v2 offset:57344
	s_waitcnt lgkmcnt(3)
	v_mfma_f32_32x32x16_bf16 v[116:131], v[244:247], v[136:139], v[116:131]
	s_waitcnt lgkmcnt(2)
	v_mfma_f32_32x32x16_bf16 v[100:115], v[248:251], v[136:139], v[100:115]
	v_sub_f32_e32 v2, v84, v234
	v_exp_f32_e32 v84, v2
	v_sub_f32_e32 v2, v68, v234
	s_waitcnt lgkmcnt(1)
	v_mfma_f32_32x32x16_bf16 v[116:131], v[252:255], v[132:135], v[116:131]
	s_waitcnt lgkmcnt(0)
	v_mfma_f32_32x32x16_bf16 v[100:115], v[236:239], v[132:135], v[100:115]
	v_exp_f32_e32 v132, v2
	v_sub_f32_e32 v2, v85, v234
	v_exp_f32_e32 v85, v2
	v_sub_f32_e32 v2, v69, v234
	v_exp_f32_e32 v133, v2
	v_sub_f32_e32 v2, v86, v234
	v_exp_f32_e32 v86, v2
	v_sub_f32_e32 v2, v70, v234
	v_exp_f32_e32 v134, v2
	v_sub_f32_e32 v2, v87, v234
	v_exp_f32_e32 v87, v2
	v_sub_f32_e32 v2, v71, v234
	v_exp_f32_e32 v135, v2
	v_sub_f32_e32 v2, v88, v234
	v_exp_f32_e32 v70, v2
	v_sub_f32_e32 v2, v72, v234
	v_exp_f32_e32 v88, v2
	v_sub_f32_e32 v2, v89, v234
	v_exp_f32_e32 v71, v2
	v_sub_f32_e32 v2, v73, v234
	v_exp_f32_e32 v89, v2
	v_sub_f32_e32 v2, v90, v234
	v_exp_f32_e32 v72, v2
	v_sub_f32_e32 v2, v74, v234
	v_exp_f32_e32 v90, v2
	v_sub_f32_e32 v2, v91, v234
	v_exp_f32_e32 v73, v2
	v_sub_f32_e32 v2, v75, v234
	v_exp_f32_e32 v91, v2
	v_sub_f32_e32 v2, v92, v234
	v_exp_f32_e32 v74, v2
	v_sub_f32_e32 v2, v76, v234
	v_exp_f32_e32 v92, v2
	v_sub_f32_e32 v2, v93, v234
	v_exp_f32_e32 v75, v2
	v_sub_f32_e32 v2, v77, v234
	v_exp_f32_e32 v93, v2
	v_sub_f32_e32 v2, v94, v234
	v_exp_f32_e32 v76, v2
	v_sub_f32_e32 v2, v78, v234
	v_exp_f32_e32 v94, v2
	v_sub_f32_e32 v2, v95, v234
	v_exp_f32_e32 v77, v2
	v_sub_f32_e32 v2, v79, v234
	v_exp_f32_e32 v95, v2
	v_sub_f32_e32 v2, v96, v234
	v_exp_f32_e32 v78, v2
	v_sub_f32_e32 v2, v80, v234
	v_exp_f32_e32 v96, v2
	v_sub_f32_e32 v2, v97, v234
	v_exp_f32_e32 v79, v2
	v_sub_f32_e32 v2, v81, v234
	v_exp_f32_e32 v97, v2
	v_sub_f32_e32 v2, v98, v234
	v_exp_f32_e32 v80, v2
	v_sub_f32_e32 v2, v82, v234
	v_exp_f32_e32 v98, v2
	v_sub_f32_e32 v2, v99, v234
	v_exp_f32_e32 v81, v2
	v_sub_f32_e32 v2, v83, v234
	v_exp_f32_e32 v99, v2
	v_pk_add_f32 v[68:69], v[76:77], v[94:95]
	v_pk_add_f32 v[82:83], v[86:87], v[134:135]
	v_pk_add_f32 v[138:139], v[72:73], v[90:91]
	v_pk_add_f32 v[136:137], v[80:81], v[98:99]
	v_pk_add_f32 v[140:141], v[74:75], v[92:93]
	v_pk_add_f32 v[142:143], v[84:85], v[132:133]
	v_pk_add_f32 v[144:145], v[78:79], v[96:97]
	v_pk_add_f32 v[146:147], v[70:71], v[88:89]
	v_pk_add_f32 v[140:141], v[142:143], v[140:141]
	v_pk_add_f32 v[144:145], v[146:147], v[144:145]
	v_pk_add_f32 v[136:137], v[138:139], v[136:137]
	v_pk_add_f32 v[68:69], v[82:83], v[68:69]
	v_pk_add_f32 v[82:83], v[140:141], v[144:145]
	v_pk_add_f32 v[68:69], v[68:69], v[136:137]
	s_nop 0
	v_pk_mov_b32 v[136:137], v[82:83], v[68:69] op_sel:[1,0]
	v_mov_b32_e32 v83, v69
	v_pk_add_f32 v[68:69], v[136:137], v[82:83]
	s_nop 0
	v_pk_add_f32 v[68:69], v[68:69], v[68:69] op_sel:[0,1] op_sel_hi:[1,0]
	s_nop 0
	v_mov_b32_e32 v2, v68
	s_nop 1
	v_permlane32_swap_b32_e32 v68, v2
	v_add_f32_e32 v2, v68, v2
	v_cvt_pk_bf16_f32 v68, v84, v85
	v_cvt_pk_bf16_f32 v69, v86, v87
	v_cvt_pk_bf16_f32 v70, v70, v71
	v_cvt_pk_bf16_f32 v71, v72, v73
	v_cvt_pk_bf16_f32 v72, v74, v75
	v_cvt_pk_bf16_f32 v73, v76, v77
	v_cvt_pk_bf16_f32 v74, v78, v79
	v_cvt_pk_bf16_f32 v75, v80, v81
	v_cvt_pk_bf16_f32 v76, v132, v133
	v_cvt_pk_bf16_f32 v77, v134, v135
	v_cvt_pk_bf16_f32 v78, v88, v89
	v_cvt_pk_bf16_f32 v79, v90, v91
	v_cvt_pk_bf16_f32 v80, v92, v93
	v_cvt_pk_bf16_f32 v81, v94, v95
	v_cvt_pk_bf16_f32 v82, v96, v97
	v_cvt_pk_bf16_f32 v83, v98, v99
	ds_read_b64_tr_b16 v[84:85], v190 offset:0
	ds_read_b64_tr_b16 v[86:87], v190 offset:0x800
	ds_read_b64_tr_b16 v[88:89], v190 offset:0x1000
	ds_read_b64_tr_b16 v[90:91], v190 offset:0x1800
	ds_read_b64_tr_b16 v[92:93], v190 offset:0x2000
	ds_read_b64_tr_b16 v[94:95], v190 offset:0x2800
	ds_read_b64_tr_b16 v[96:97], v190 offset:0x3000
	ds_read_b64_tr_b16 v[98:99], v190 offset:0x3800
	s_waitcnt lgkmcnt(0)
	v_add_f32_e32 v2, v232, v2
	v_permlane32_swap_b32_e32 v68, v70
	v_permlane32_swap_b32_e32 v69, v71
	v_permlane32_swap_b32_e32 v72, v74
	v_permlane32_swap_b32_e32 v73, v75
	v_permlane32_swap_b32_e32 v76, v78
	v_permlane32_swap_b32_e32 v77, v79
	v_permlane32_swap_b32_e32 v80, v82
	v_permlane32_swap_b32_e32 v81, v83
	v_mfma_f32_32x32x16_bf16 v[52:67], v[84:87], v[68:71], v[52:67]
	ds_read_b64_tr_b16 v[84:85], v190 offset:0x200
	ds_read_b64_tr_b16 v[86:87], v190 offset:0xa00
	v_mfma_f32_32x32x16_bf16 v[52:67], v[88:91], v[72:75], v[52:67]
	ds_read_b64_tr_b16 v[88:89], v190 offset:0x1200
	ds_read_b64_tr_b16 v[90:91], v190 offset:0x1a00
	v_mfma_f32_32x32x16_bf16 v[52:67], v[92:95], v[76:79], v[52:67]
	ds_read_b64_tr_b16 v[92:93], v190 offset:0x2200
	ds_read_b64_tr_b16 v[94:95], v190 offset:0x2a00
	ds_read_b64_tr_b16 v[132:133], v190 offset:0x3200
	ds_read_b64_tr_b16 v[134:135], v190 offset:0x3a00
	s_waitcnt lgkmcnt(0)
	v_mfma_f32_32x32x16_bf16 v[52:67], v[96:99], v[80:83], v[52:67]
	v_mfma_f32_32x32x16_bf16 v[36:51], v[84:87], v[68:71], v[36:51]
	ds_read_b64_tr_b16 v[84:85], v190 offset:0x400
	ds_read_b64_tr_b16 v[86:87], v190 offset:0xc00
	v_mfma_f32_32x32x16_bf16 v[36:51], v[88:91], v[72:75], v[36:51]
	ds_read_b64_tr_b16 v[88:89], v190 offset:0x1400
	ds_read_b64_tr_b16 v[90:91], v190 offset:0x1c00
	v_mfma_f32_32x32x16_bf16 v[36:51], v[92:95], v[76:79], v[36:51]
	ds_read_b64_tr_b16 v[92:93], v190 offset:0x2400
	ds_read_b64_tr_b16 v[94:95], v190 offset:0x2c00
	ds_read_b64_tr_b16 v[96:97], v190 offset:0x3400
	ds_read_b64_tr_b16 v[98:99], v190 offset:0x3c00
	s_waitcnt lgkmcnt(0)
	v_mfma_f32_32x32x16_bf16 v[36:51], v[132:135], v[80:83], v[36:51]
	v_mfma_f32_32x32x16_bf16 v[20:35], v[84:87], v[68:71], v[20:35]
	ds_read_b64_tr_b16 v[84:85], v190 offset:0x600
	ds_read_b64_tr_b16 v[86:87], v190 offset:0xe00
	v_mfma_f32_32x32x16_bf16 v[20:35], v[88:91], v[72:75], v[20:35]
	ds_read_b64_tr_b16 v[88:89], v190 offset:0x1600
	ds_read_b64_tr_b16 v[90:91], v190 offset:0x1e00
	v_mfma_f32_32x32x16_bf16 v[20:35], v[92:95], v[76:79], v[20:35]
	ds_read_b64_tr_b16 v[92:93], v190 offset:0x2600
	ds_read_b64_tr_b16 v[94:95], v190 offset:0x2e00
	ds_read_b64_tr_b16 v[132:133], v190 offset:0x3600
	ds_read_b64_tr_b16 v[134:135], v190 offset:0x3e00
	s_waitcnt lgkmcnt(0)
	v_mfma_f32_32x32x16_bf16 v[20:35], v[96:99], v[80:83], v[20:35]
	v_mfma_f32_32x32x16_bf16 v[4:19], v[84:87], v[68:71], v[4:19]
	v_max_f32_e32 v96, v117, v117
	v_max_f32_e32 v97, v116, v116
	v_max_f32_e32 v96, v97, v96
	v_max3_f32 v96, v96, v118, v119
	v_max3_f32 v96, v96, v120, v121
	v_max3_f32 v68, v96, v122, v123
	v_max3_f32 v68, v68, v124, v125
	v_mfma_f32_32x32x16_bf16 v[4:19], v[88:91], v[72:75], v[4:19]
	v_max3_f32 v68, v68, v126, v127
	v_max3_f32 v68, v68, v128, v129
	v_max3_f32 v68, v68, v130, v131
	v_max3_f32 v68, v68, v100, v101
	v_max3_f32 v68, v68, v102, v103
	v_max3_f32 v68, v68, v104, v105
	v_max3_f32 v68, v68, v106, v107
	v_mfma_f32_32x32x16_bf16 v[4:19], v[92:95], v[76:79], v[4:19]
	v_max3_f32 v68, v68, v108, v109
	v_max3_f32 v68, v68, v110, v111
	v_max3_f32 v68, v68, v112, v113
	v_max3_f32 v68, v68, v114, v115
	v_mov_b32_e32 v69, v68
	s_nop 1
	v_permlane32_swap_b32_e32 v68, v69
	v_mfma_f32_32x32x16_bf16 v[4:19], v[132:135], v[80:83], v[4:19]
	v_max_f32_e32 v69, v69, v69
	v_max_f32_e32 v68, v68, v68
	v_max_f32_e32 v68, v68, v69
	v_cmp_lt_f32_e32 vcc, s89, v68
	s_or_b64 vcc, s[12:13], vcc
	s_cbranch_vccz .LBB0_1046
	v_cndmask_b32_e32 v228, 0, v68, vcc
	v_exp_f32_e64 v68, -v228
	v_cndmask_b32_e64 v69, v222, 0, s[12:13]
	v_add_f32_e32 v222, v69, v228
	v_cndmask_b32_e64 v68, v68, 0, s[12:13]
	v_mul_f32_e32 v2, v2, v68
	v_pk_mul_f32 v[66:67], v[66:67], v[68:69] op_sel_hi:[1,0]
	v_pk_mul_f32 v[64:65], v[64:65], v[68:69] op_sel_hi:[1,0]
	v_pk_mul_f32 v[62:63], v[62:63], v[68:69] op_sel_hi:[1,0]
	v_pk_mul_f32 v[60:61], v[60:61], v[68:69] op_sel_hi:[1,0]
	v_pk_mul_f32 v[58:59], v[58:59], v[68:69] op_sel_hi:[1,0]
	v_pk_mul_f32 v[56:57], v[56:57], v[68:69] op_sel_hi:[1,0]
	v_pk_mul_f32 v[54:55], v[54:55], v[68:69] op_sel_hi:[1,0]
	v_pk_mul_f32 v[52:53], v[52:53], v[68:69] op_sel_hi:[1,0]
	v_pk_mul_f32 v[50:51], v[50:51], v[68:69] op_sel_hi:[1,0]
	v_pk_mul_f32 v[48:49], v[48:49], v[68:69] op_sel_hi:[1,0]
	v_pk_mul_f32 v[46:47], v[46:47], v[68:69] op_sel_hi:[1,0]
	v_pk_mul_f32 v[44:45], v[44:45], v[68:69] op_sel_hi:[1,0]
	v_pk_mul_f32 v[42:43], v[42:43], v[68:69] op_sel_hi:[1,0]
	v_pk_mul_f32 v[40:41], v[40:41], v[68:69] op_sel_hi:[1,0]
	v_pk_mul_f32 v[38:39], v[38:39], v[68:69] op_sel_hi:[1,0]
	v_pk_mul_f32 v[36:37], v[36:37], v[68:69] op_sel_hi:[1,0]
	v_pk_mul_f32 v[34:35], v[34:35], v[68:69] op_sel_hi:[1,0]
	v_pk_mul_f32 v[32:33], v[32:33], v[68:69] op_sel_hi:[1,0]
	v_pk_mul_f32 v[30:31], v[30:31], v[68:69] op_sel_hi:[1,0]
	v_pk_mul_f32 v[28:29], v[28:29], v[68:69] op_sel_hi:[1,0]
	v_pk_mul_f32 v[26:27], v[26:27], v[68:69] op_sel_hi:[1,0]
	v_pk_mul_f32 v[24:25], v[24:25], v[68:69] op_sel_hi:[1,0]
	v_pk_mul_f32 v[22:23], v[22:23], v[68:69] op_sel_hi:[1,0]
	v_pk_mul_f32 v[20:21], v[20:21], v[68:69] op_sel_hi:[1,0]
	v_pk_mul_f32 v[18:19], v[18:19], v[68:69] op_sel_hi:[1,0]
	v_pk_mul_f32 v[16:17], v[16:17], v[68:69] op_sel_hi:[1,0]
	v_pk_mul_f32 v[14:15], v[14:15], v[68:69] op_sel_hi:[1,0]
	v_pk_mul_f32 v[12:13], v[12:13], v[68:69] op_sel_hi:[1,0]
	v_pk_mul_f32 v[10:11], v[10:11], v[68:69] op_sel_hi:[1,0]
	v_pk_mul_f32 v[8:9], v[8:9], v[68:69] op_sel_hi:[1,0]
	v_pk_mul_f32 v[6:7], v[6:7], v[68:69] op_sel_hi:[1,0]
	v_pk_mul_f32 v[4:5], v[4:5], v[68:69] op_sel_hi:[1,0]

	.amdhsa_kernel _Z13hawk_moba_fwd4Args
		.amdhsa_group_segment_fixed_size 0
		.amdhsa_private_segment_fixed_size 0
		.amdhsa_kernarg_size 424
		.amdhsa_user_sgpr_count 2
		.amdhsa_user_sgpr_dispatch_ptr 0
		.amdhsa_user_sgpr_queue_ptr 0
		.amdhsa_user_sgpr_kernarg_segment_ptr 1
		.amdhsa_user_sgpr_dispatch_id 0
		.amdhsa_user_sgpr_kernarg_preload_length 0
		.amdhsa_user_sgpr_kernarg_preload_offset 0
		.amdhsa_user_sgpr_private_segment_size 0
		.amdhsa_uses_dynamic_stack 0
		.amdhsa_enable_private_segment 0
		.amdhsa_system_sgpr_workgroup_id_x 1
		.amdhsa_system_sgpr_workgroup_id_y 0
		.amdhsa_system_sgpr_workgroup_id_z 0
		.amdhsa_system_sgpr_workgroup_info 0
		.amdhsa_system_vgpr_workitem_id 0
		.amdhsa_next_free_vgpr 256
		.amdhsa_next_free_sgpr 98
		.amdhsa_accum_offset 256
		.amdhsa_reserve_vcc 1
		.amdhsa_float_round_mode_32 0
		.amdhsa_float_round_mode_16_64 0
		.amdhsa_float_denorm_mode_32 3
		.amdhsa_float_denorm_mode_16_64 3
		.amdhsa_dx10_clamp 1
		.amdhsa_ieee_mode 1
		.amdhsa_fp16_overflow 0
		.amdhsa_tg_split 0
		.amdhsa_exception_fp_ieee_invalid_op 0
		.amdhsa_exception_fp_denorm_src 0
		.amdhsa_exception_fp_ieee_div_zero 0
		.amdhsa_exception_fp_ieee_overflow 0
		.amdhsa_exception_fp_ieee_underflow 0
		.amdhsa_exception_fp_ieee_inexact 0
		.amdhsa_exception_int_div_zero 0
	.end_amdhsa_kernel

amdhsa.kernels:
  - .agpr_count:     0
    .args:
      - .offset:         0
        .size:           168
        .value_kind:     by_value
      - .offset:         168
        .size:           4
        .value_kind:     hidden_block_count_x
      - .offset:         172
        .size:           4
        .value_kind:     hidden_block_count_y
      - .offset:         176
        .size:           4
        .value_kind:     hidden_block_count_z
      - .offset:         180
        .size:           2
        .value_kind:     hidden_group_size_x
      - .offset:         182
        .size:           2
        .value_kind:     hidden_group_size_y
      - .offset:         184
        .size:           2
        .value_kind:     hidden_group_size_z
      - .offset:         186
        .size:           2
        .value_kind:     hidden_remainder_x
      - .offset:         188
        .size:           2
        .value_kind:     hidden_remainder_y
      - .offset:         190
        .size:           2
        .value_kind:     hidden_remainder_z
      - .offset:         208
        .size:           8
        .value_kind:     hidden_global_offset_x
      - .offset:         216
        .size:           8
        .value_kind:     hidden_global_offset_y
      - .offset:         224
        .size:           8
        .value_kind:     hidden_global_offset_z
      - .offset:         232
        .size:           2
        .value_kind:     hidden_grid_dims
      - .offset:         288
        .size:           4
        .value_kind:     hidden_dynamic_lds_size
    .group_segment_fixed_size: 0
    .kernarg_segment_align: 8
    .kernarg_segment_size: 424
    .language:       OpenCL C
    .language_version:
      - 2
      - 0
    .max_flat_workgroup_size: 512
    .name:           _Z13hawk_moba_fwd4Args
    .private_segment_fixed_size: 0
    .sgpr_count:     104
    .sgpr_spill_count: 0
    .symbol:         _Z13hawk_moba_fwd4Args.kd
    .uniform_work_group_size: 1
    .uses_dynamic_stack: false
    .vgpr_count:     256
    .vgpr_spill_count: 0
    .wavefront_size: 64
